# barrier: counter polling (all waiters watch the global arrival counter) combined with mid-arriver early L2 writeback
# baseline (speedup 1.0000x reference)
.Lbar_noflush:
	s_nop 0
	v_add3_u32 v0, s2, v0, 1
	v_readlane_b32 s2, v255, 6
	s_mul_i32 s2, s3, s2
	s_nop 0
	v_cmp_ne_u32_e32 vcc, s2, v0
	s_and_saveexec_b64 s[2:3], vcc
	s_xor_b64 s[2:3], exec, s[2:3]
	s_cbranch_execz .LBB0_1047
	v_readlane_b32 s4, v254, 21
	v_readlane_b32 s5, v254, 22
	v_readlane_b32 s6, v255, 10
	v_readlane_b32 s99, v254, 61
	s_mul_i32 s6, s6, s99
	s_nop 3
	global_load_dword v0, v193, s[4:5] sc1
	s_waitcnt vmcnt(0)
	v_cmp_le_u32_e32 vcc, s6, v0
	s_cbranch_vccnz .LBB0_1046
